# scan group 1 spread over 128 workgroups, one active half each (shared staging duplicated)
# baseline (speedup 1.0000x reference)
; DEV int vhalf() { return __builtin_amdgcn_readfirstlane((int)(threadIdx.x >> 8)); }
; DEV void phase_p2_naive(const Params& p, int g, char* hsm) {
;   __shared__ int s_item;
;   const int nscan = g ? 128 : 256;
;   const int nhy = 1024;
;   unsigned* cnt = (unsigned*)(p.ws + OFF_CNT) + g;
;   const int half = vhalf();
;   if ((int)blockIdx.x * 2 < nscan) scan_item_mfma(p, g, blockIdx.x * 2 + half, hsm);
.LBB0_667:
	s_movk_i32 s40, 0x1400
	s_or_b64 exec, exec, s[0:1]
	s_and_b64 s[0:1], s[66:67], exec
	v_readfirstlane_b32 s24, v202
	s_movk_i32 s0, 0x100
	s_lshr_b32 s26, s24, 8
	s_cmp_ge_i32 s81, s0
	s_waitcnt lgkmcnt(0)
	s_barrier
	s_cbranch_scc1 .LBB0_720
	v_writelane_b32 v160, s0, 0
	v_writelane_b32 v160, s1, 1
	v_writelane_b32 v160, s2, 2
	v_writelane_b32 v160, s3, 3
	v_writelane_b32 v160, s4, 4
	v_writelane_b32 v160, s5, 5
	v_writelane_b32 v160, s6, 6
	v_writelane_b32 v160, s7, 7
	v_writelane_b32 v160, s8, 8
	v_writelane_b32 v160, s9, 9
	v_writelane_b32 v160, s10, 10
	v_writelane_b32 v160, s11, 11
	v_writelane_b32 v160, s12, 12
	v_writelane_b32 v160, s13, 13
	v_writelane_b32 v160, s14, 14
	v_writelane_b32 v160, s15, 15
	v_writelane_b32 v160, s16, 16
	v_writelane_b32 v160, s17, 17
	v_writelane_b32 v160, s18, 18
	v_writelane_b32 v160, s19, 19
	v_writelane_b32 v160, s20, 20
	v_writelane_b32 v160, s21, 21
	v_writelane_b32 v160, s22, 22
	v_writelane_b32 v160, s23, 23
	v_writelane_b32 v160, s24, 24
	v_writelane_b32 v160, s25, 25
	v_writelane_b32 v160, s26, 26
	v_writelane_b32 v160, s27, 27
	v_writelane_b32 v160, s28, 28
	v_writelane_b32 v160, s29, 29
	v_writelane_b32 v160, s30, 30
	v_writelane_b32 v160, s31, 31
	v_writelane_b32 v160, s33, 33
	v_writelane_b32 v160, s34, 34
	v_writelane_b32 v160, s35, 35
	v_writelane_b32 v160, s36, 36
	v_writelane_b32 v160, s37, 37
	v_writelane_b32 v160, s38, 38
	v_writelane_b32 v160, s39, 39
	v_writelane_b32 v160, s40, 40
	v_writelane_b32 v160, s41, 41
	v_writelane_b32 v160, s42, 42
	v_writelane_b32 v160, s43, 43
	v_writelane_b32 v160, s44, 44
	v_writelane_b32 v160, s45, 45
	v_writelane_b32 v160, s46, 46
	v_writelane_b32 v160, s47, 47
	v_writelane_b32 v160, s48, 48
	v_writelane_b32 v160, s49, 49
	v_writelane_b32 v160, s50, 50
	v_writelane_b32 v160, s51, 51
	v_writelane_b32 v160, s52, 52
	v_writelane_b32 v160, s53, 53
	v_writelane_b32 v160, s54, 54
	v_writelane_b32 v160, s55, 55
	v_writelane_b32 v160, s56, 56
	v_writelane_b32 v160, s57, 57
	v_writelane_b32 v160, s58, 58
	v_writelane_b32 v160, s59, 59
	v_writelane_b32 v160, s60, 60
	v_writelane_b32 v160, s61, 61
	v_writelane_b32 v160, s62, 62
	v_writelane_b32 v160, s63, 63
	v_writelane_b32 v161, s64, 0
	v_writelane_b32 v161, s65, 1
	v_writelane_b32 v161, s66, 2
	v_writelane_b32 v161, s67, 3
	v_writelane_b32 v161, s68, 4
	v_writelane_b32 v161, s69, 5
	v_writelane_b32 v161, s70, 6
	v_writelane_b32 v161, s71, 7
	v_writelane_b32 v161, s72, 8
	v_writelane_b32 v161, s73, 9
	s_barrier
	s_add_i32 s2, s26, s81
	s_mov_b32 s27, 1
	s_and_b64 s[0:1], s[66:67], exec
	s_cbranch_scc1 .Lscan_g0map
	s_lshr_b32 s2, s81, 2
	s_lshl_b32 s2, s2, 1
	s_add_i32 s2, s2, s26
	s_bfe_u32 s0, s81, 0x10001
	s_cmp_eq_u32 s0, s26
	s_cselect_b32 s27, 1, 0
; DEV int tidx() { return tidx_full() & 255; }
; DEV void scan_item_mfma(const Params& p, int g, int item, char* smem) {
;   const int L = g ? 8192 : 4096;
;   const int NC = L / 64;
;   const int vs = item & 3, dir = (item >> 2) & 1, h = (item >> 3) & 3, b = item >> 5;
;   char* Qs = smem;
;   char* Ks = Qs + 17408;
;   char* KTs = Ks + 17408;
;   char* Vts = KTs + 18432;
;   char* Ps = Vts + 4608;
;   char* Sts = Ps + 9216;
;   float* decs = (float*)(Sts + 8704);
;   u16* PHG = (u16*)(p.ws + OFF_PHG);
;   const u16* QK = (const u16*)(p.out + (size_t)g * NTOK * D);
;   const u16* Qp = QK + (size_t)(2 * dir) * NTOK * 512;
;   const u16* Kp = Qp + (size_t)NTOK * 512;
;   const u16* KT = (const u16*)(p.ws + OFF_KT);
;   const float* DEC = (const float*)(p.ws + OFF_DEC);
;   const int tid = tidx();
;   const int wave = __builtin_amdgcn_readfirstlane(tid >> 6);
;   const int lane = tid & 63, r = lane & 31, hh = lane >> 5;
;   __syncthreads();
;   for (int e = tid; e < 8704 / 16; e += 256) ((uint4*)Sts)[e] = make_uint4(0, 0, 0, 0);
;   f32x16 accS[2];
; #pragma unroll
;   for (int t = 0; t < 2; ++t)
; #pragma unroll
;     for (int i = 0; i < 16; ++i) accS[t][i] = 0.f;
;   const int ocol = (dir ? 1024 : 0) + h * 128 + vs * 32;
;   uint4 q0, q1, q2, q3, k0, k1, k2, k3, t0, t1, t2, t3, vv;
;   float dd = 0.f;
;   const int qrow = tid >> 4, qc = tid & 15;
;   const int trow = tid >> 3, tc = tid & 7;
;   const int vrow = tid >> 2, vc = tid & 3;
;     ...
;   unsigned opk[8] = {0u, 0u, 0u, 0u, 0u, 0u, 0u, 0u};
;   size_t otok = 0;
;   SCAN_ISSUE(dir ? NC - 1 : 0);
.Lscan_g0map:
	s_and_b32 s3, s2, 3
	s_bfe_u32 s4, s2, 0x10002
	s_bfe_u32 s5, s2, 0x20003
	s_lshr_b32 s6, s2, 5
	s_and_b64 s[0:1], s[66:67], exec
	s_cselect_b32 s7, 64, 0x80
	s_bfe_u32 s9, s24, 0x20006
	s_mul_i32 s31, s26, 0x3600
	s_add_u32 s31, s31, 0xf400
	v_and_b32_e32 v53, 0xff, v202
	v_and_b32_e32 v54, 63, v202
	v_and_b32_e32 v55, 31, v202
	v_bfe_u32 v109, v202, 5, 1
	v_bfe_u32 v110, v202, 6, 2
	v_and_b32_e32 v111, 0x1ff, v202
	v_lshrrev_b32_e32 v220, 4, v111
	v_and_b32_e32 v221, 15, v111
	v_lshlrev_b32_e32 v219, 4, v221
	v_lshl_add_u32 v209, v220, 10, v219
	v_add_u32_e32 v210, 0x8000, v209
	v_mul_u32_u24_e32 v248, 0x110, v220
	v_add_u32_e32 v234, v248, v219
	v_lshrrev_b32_e32 v220, 3, v111
	v_and_b32_e32 v221, 7, v111
	v_lshlrev_b32_e32 v219, 4, v221
	v_lshl_add_u32 v213, v220, 7, v219
	v_add_u32_e32 v214, 0x2000, v213
	v_mul_u32_u24_e32 v248, 0x90, v220
	v_add_u32_e32 v235, v248, v219
	v_lshrrev_b32_e32 v220, 2, v53
	v_and_b32_e32 v221, 3, v53
	v_mul_u32_u24_e32 v219, 0x1400, v220
	v_lshl_add_u32 v215, v221, 4, v219
	v_mul_u32_u24_e32 v219, 0x480, v221
	v_lshl_add_u32 v219, v220, 1, v219
	v_add_u32_e32 v236, s31, v219
	v_and_b32_e32 v220, 0x7f, v53
	v_lshlrev_b32_e32 v216, 2, v220
	v_add_u32_e32 v237, s31, v216
	v_mul_u32_u24_e32 v220, 0x110, v55
	v_mul_u32_u24_e32 v221, 0x90, v55
	v_lshlrev_b32_e32 v219, 4, v109
	v_add_u32_e32 v164, v220, v219
	v_add3_u32 v245, v220, v219, s31
	v_add3_u32 v244, v221, v219, s31
	v_add_u32_e32 v111, v221, v219
	v_lshrrev_b32_e32 v248, 1, v110
	v_mul_u32_u24_e32 v248, 0x2200, v248
	v_add_u32_e32 v240, v164, v248
	v_and_b32_e32 v248, 1, v110
	v_mul_u32_u24_e32 v248, 0x2200, v248
	v_add_u32_e32 v242, v164, v248
	v_mul_u32_u24_e32 v248, 0x2200, v110
	v_add_u32_e32 v241, v164, v248
	v_mul_u32_u24_e32 v248, 0x1200, v110
	v_add_u32_e32 v243, v111, v248
	v_lshrrev_b32_e32 v248, 1, v110
	v_mul_u32_u24_e32 v248, 0x1200, v248
	v_add_u32_e32 v239, v221, v248
	v_and_b32_e32 v248, 1, v110
	v_lshlrev_b32_e32 v248, 6, v248
	v_lshl_add_u32 v248, v109, 3, v248
	v_add_u32_e32 v239, v239, v248
	v_subrev_u32_e32 v248, 2, v110
	v_lshlrev_b32_e32 v219, 7, v248
	v_lshl_add_u32 v219, v109, 3, v219
	v_add3_u32 v238, v220, v219, s31
	v_mul_u32_u24_e32 v219, 0x2400, v248
	v_add_u32_e32 v207, v111, v219
	v_lshlrev_b32_e32 v219, 8, v248
	v_lshl_add_u32 v219, v109, 4, v219
	v_add_u32_e32 v208, s31, v219
	v_lshl_add_u32 v219, v110, 5, v55
	v_mul_u32_u24_e32 v219, 0x1400, v219
	v_lshl_add_u32 v217, v109, 3, v219
	v_lshlrev_b32_e32 v219, 2, v109
	v_sub_u32_e32 v218, v55, v219
	s_cmp_eq_u32 s4, 0
	s_cbranch_scc0 .Lscan_d1
	s_mul_i32 s11, s6, s7
	s_mov_b32 s12, s64
	s_mov_b32 s13, s65
	s_mul_i32 s0, s11, 0x10000
	s_add_u32 s12, s12, s0
	s_addc_u32 s13, s13, 0
	s_mul_i32 s0, s5, 0x100
	s_add_u32 s12, s12, s0
	s_addc_u32 s13, s13, 0
	s_add_u32 s14, s12, 0x2000000
	s_addc_u32 s15, s13, 0
	s_add_u32 s16, s88, 0x3d4c100
	s_addc_u32 s17, s89, 0
	s_mul_i32 s0, s11, 0x20000
	s_add_u32 s16, s16, s0
	s_addc_u32 s17, s17, 0
	s_mul_i32 s0, s5, 0x4000
	s_add_u32 s16, s16, s0
	s_addc_u32 s17, s17, 0
	s_add_u32 s18, s88, 0xdd4c500
	s_addc_u32 s19, s89, 0
	s_mul_i32 s0, s11, 0x50000
	s_add_u32 s18, s18, s0
	s_addc_u32 s19, s19, 0
	s_mul_i32 s0, s5, 0x100
	s_add_u32 s18, s18, s0
	s_addc_u32 s19, s19, 0
	s_mul_i32 s0, s3, 0x40
	s_add_u32 s18, s18, s0
	s_addc_u32 s19, s19, 0
	s_add_u32 s20, s88, 0x3b4c100
	s_addc_u32 s21, s89, 0
	s_mul_i32 s0, s11, 0x800
	s_add_u32 s20, s20, s0
	s_addc_u32 s21, s21, 0
	s_mul_i32 s0, s5, 0x200
	s_add_u32 s20, s20, s0
	s_addc_u32 s21, s21, 0
	s_add_u32 s22, s88, 0xdd4c100
	s_addc_u32 s23, s89, 0
	s_mul_i32 s0, s11, 0x50000
	s_add_u32 s22, s22, s0
	s_addc_u32 s23, s23, 0
	s_mul_i32 s0, s5, 0x100
	s_add_u32 s22, s22, s0
	s_addc_u32 s23, s23, 0
	s_mul_i32 s0, s3, 0x40
	s_add_u32 s22, s22, s0
	s_addc_u32 s23, s23, 0
	v_cmp_le_i32_e64 s[34:35], 0, v218
	v_cmp_le_i32_e64 s[36:37], 1, v218
	v_cmp_le_i32_e64 s[38:39], 2, v218
	v_cmp_le_i32_e64 s[40:41], 3, v218
	v_cmp_le_i32_e64 s[42:43], 8, v218
	v_cmp_le_i32_e64 s[44:45], 9, v218
	v_cmp_le_i32_e64 s[46:47], 10, v218
	v_cmp_le_i32_e64 s[48:49], 11, v218
	v_cmp_le_i32_e64 s[50:51], 16, v218
	v_cmp_le_i32_e64 s[52:53], 17, v218
	v_cmp_le_i32_e64 s[54:55], 18, v218
	v_cmp_le_i32_e64 s[56:57], 19, v218
	v_cmp_le_i32_e64 s[58:59], 24, v218
	v_cmp_le_i32_e64 s[60:61], 25, v218
	v_cmp_le_i32_e64 s[62:63], 26, v218
	v_cmp_le_i32_e64 s[64:65], 27, v218
	v_mov_b32_e32 v144, 0
	v_mov_b32_e32 v145, 0
	v_mov_b32_e32 v146, 0
	v_mov_b32_e32 v147, 0
	v_mov_b64_e32 v[112:113], v[144:145]
	v_mov_b64_e32 v[114:115], v[144:145]
	v_mov_b64_e32 v[116:117], v[144:145]
	v_mov_b64_e32 v[118:119], v[144:145]
	v_mov_b64_e32 v[120:121], v[144:145]
	v_mov_b64_e32 v[122:123], v[144:145]
	v_mov_b64_e32 v[124:125], v[144:145]
	v_mov_b64_e32 v[126:127], v[144:145]
	v_mov_b64_e32 v[128:129], v[144:145]
	v_mov_b64_e32 v[130:131], v[144:145]
	v_mov_b64_e32 v[132:133], v[144:145]
	v_mov_b64_e32 v[134:135], v[144:145]
	v_mov_b64_e32 v[136:137], v[144:145]
	v_mov_b64_e32 v[138:139], v[144:145]
	v_mov_b64_e32 v[140:141], v[144:145]
	v_mov_b64_e32 v[142:143], v[144:145]
	v_lshl_add_u32 v220, v53, 5, s31
	ds_write_b128 v220, v[144:147] offset:4608
	ds_write_b128 v220, v[144:147] offset:4624
	v_and_b32_e32 v221, 31, v53
	v_lshl_add_u32 v221, v221, 4, s31
	ds_write_b128 v221, v[144:147] offset:12800
	s_cmp_eq_u32 s26, 0
	s_cbranch_scc0 .Lsc0_nz
	s_cmp_eq_u32 s9, 1
	s_cbranch_scc0 .Lsc0_nz
	v_mul_u32_u24_e32 v219, 24, v109
	v_add_u32_e32 v219, v239, v219
	ds_write_b128 v219, v[144:147] offset:53248
	ds_write_b128 v219, v[144:147] offset:53264
.Lsc0_nz:
	s_mov_b32 s25, s9
	s_cmp_eq_u32 s9, 1
	s_cselect_b32 s25, 4, s25
	s_cmp_eq_u32 s26, 0
	s_cselect_b32 s25, s25, 4
	s_cmp_eq_u32 s27, 0
	s_cselect_b32 s0, 2, 0
	s_or_b32 s9, s9, s0
	global_load_dwordx4 v[0:3], v209, s[12:13]
	global_load_dwordx4 v[4:7], v210, s[12:13]
	global_load_dwordx4 v[8:11], v209, s[14:15]
	global_load_dwordx4 v[12:15], v210, s[14:15]
	global_load_dwordx4 v[16:19], v213, s[16:17]
	global_load_dwordx4 v[20:23], v214, s[16:17]
	global_load_dwordx4 v[24:27], v215, s[18:19]
	global_load_dword v28, v216, s[20:21]
	s_sub_i32 s10, s7, 1
	s_cmp_gt_i32 s10, 0
	s_cselect_b32 s1, 1, 0
	s_sub_i32 s10, s10, s1
	s_mul_i32 s0, s1, 0x10000
	s_add_u32 s12, s12, s0
	s_addc_u32 s13, s13, 0
	s_mul_i32 s0, s1, 0x10000
	s_add_u32 s14, s14, s0
	s_addc_u32 s15, s15, 0
	s_mul_i32 s0, s1, 0x20000
	s_add_u32 s16, s16, s0
	s_addc_u32 s17, s17, 0
	s_mul_i32 s0, s1, 0x50000
	s_add_u32 s18, s18, s0
	s_addc_u32 s19, s19, 0
	s_mul_i32 s0, s1, 0x800
	s_add_u32 s20, s20, s0
	s_addc_u32 s21, s21, 0
	global_load_dwordx4 v[32:35], v209, s[12:13]
	global_load_dwordx4 v[36:39], v210, s[12:13]
	global_load_dwordx4 v[40:43], v209, s[14:15]
	global_load_dwordx4 v[44:47], v210, s[14:15]
	global_load_dwordx4 v[48:51], v213, s[16:17]
	global_load_dwordx4 v[52:55], v214, s[16:17]
	global_load_dwordx4 v[56:59], v215, s[18:19]
	global_load_dword v60, v216, s[20:21]
	s_cmp_lt_u32 s9, 2
	s_cbranch_scc0 .Lsc0_w1sfa
	s_waitcnt vmcnt(8)
	s_branch .Lsc0_w1efa

; DEV void scan_item_mfma(const Params& p, int g, int item, char* smem) {
;     ...
;     {
;       char* d = Qs + qrow * 272 + qc * 16;
;       *(uint4*)(d) = q0; *(uint4*)(d + 16 * 272) = q1; *(uint4*)(d + 32 * 272) = q2; *(uint4*)(d + 48 * 272) = q3;
;       d = Ks + qrow * 272 + qc * 16;
;       *(uint4*)(d) = k0; *(uint4*)(d + 16 * 272) = k1; *(uint4*)(d + 32 * 272) = k2; *(uint4*)(d + 48 * 272) = k3;
;       d = KTs + trow * 144 + tc * 16;
;       *(uint4*)(d) = t0; *(uint4*)(d + 32 * 144) = t1; *(uint4*)(d + 64 * 144) = t2; *(uint4*)(d + 96 * 144) = t3;
;       st8t(Vts + (vc * 8) * 144 + vrow * 2, vv);
;       if (tid < 128) decs[tid] = dd;
;       if (wave < 2 && ci > 0) {
;         u16* og = PHG + (otok + 32 * wave + 4 * hh) * 2560 + ocol + r;
; #pragma unroll
;         for (int i = 0; i < 8; ++i) {
;           og[(size_t)(((2 * i) & 3) + 8 * ((2 * i) >> 2)) * 2560] = (u16)(opk[i] & 0xffffu);
;           og[(size_t)(((2 * i + 1) & 3) + 8 * ((2 * i + 1) >> 2)) * 2560] = (u16)(opk[i] >> 16);
;         }
;       }
;       if (wave >= 2 && ci > 0) {
; #pragma unroll
;         for (int t = 0; t < 2; ++t) {
;           const int kt = 2 * (wave - 2) + t;
; #pragma unroll
;           for (int rg = 0; rg < 4; ++rg) {
;             const int kk0 = 32 * kt + 8 * rg + 4 * hh;
;             *(uint2*)(Sts + r * 272 + kk0 * 2) = make_uint2(pack2(accS[t][4 * rg + 0], accS[t][4 * rg + 1]),
;                                                             pack2(accS[t][4 * rg + 2], accS[t][4 * rg + 3]));
;           }
;         }
;       }
.Lsc0_w1efa:
	ds_write_b128 v234, v[0:3] offset:0
	ds_write_b128 v234, v[4:7] offset:8704
	ds_write_b128 v234, v[8:11] offset:17408
	ds_write_b128 v234, v[12:15] offset:26112
	ds_write_b128 v235, v[16:19] offset:34816
	ds_write_b128 v235, v[20:23] offset:44032
	s_cmp_eq_u32 s27, 0
	s_cbranch_scc1 .Lsc0_p1ofa
	ds_write_b16 v236, v24 offset:0
	ds_write_b16_d16_hi v236, v24 offset:144
	ds_write_b16 v236, v25 offset:288
	ds_write_b16_d16_hi v236, v25 offset:432
	ds_write_b16 v236, v26 offset:576
	ds_write_b16_d16_hi v236, v26 offset:720
	ds_write_b16 v236, v27 offset:864
	ds_write_b16_d16_hi v236, v27 offset:1008
	ds_write_b32 v237, v28 offset:13312
	s_cmp_lt_u32 s9, 2
	s_cbranch_scc1 .Lsc0_p1ofa
	v_cvt_pk_bf16_f32 v166, v112, v113
	v_cvt_pk_bf16_f32 v167, v114, v115
	ds_write_b64 v238, v[166:167] offset:4608
	v_cvt_pk_bf16_f32 v168, v116, v117
	v_cvt_pk_bf16_f32 v169, v118, v119
	ds_write_b64 v238, v[168:169] offset:4624
	v_cvt_pk_bf16_f32 v170, v120, v121
	v_cvt_pk_bf16_f32 v171, v122, v123
	ds_write_b64 v238, v[170:171] offset:4640
	v_cvt_pk_bf16_f32 v172, v124, v125
	v_cvt_pk_bf16_f32 v173, v126, v127
	ds_write_b64 v238, v[172:173] offset:4656
	v_cvt_pk_bf16_f32 v174, v128, v129
	v_cvt_pk_bf16_f32 v175, v130, v131
	ds_write_b64 v238, v[174:175] offset:4672
	v_cvt_pk_bf16_f32 v176, v132, v133
	v_cvt_pk_bf16_f32 v177, v134, v135
	ds_write_b64 v238, v[176:177] offset:4688
	v_cvt_pk_bf16_f32 v178, v136, v137
	v_cvt_pk_bf16_f32 v179, v138, v139
	ds_write_b64 v238, v[178:179] offset:4704
	v_cvt_pk_bf16_f32 v180, v140, v141
	v_cvt_pk_bf16_f32 v181, v142, v143
	ds_write_b64 v238, v[180:181] offset:4720

; #define SCAN_BAR()                                        \
;   {                                                       \
;     asm volatile("s_waitcnt lgkmcnt(0)" ::: "memory");     \
;     __builtin_amdgcn_s_barrier();                         \
;     asm volatile("" ::: "memory");                         \
;   }
; DEV void scan_item_mfma(const Params& p, int g, int item, char* smem) {
;     ...
;     SCAN_BAR();
;     if (wave < 2) {
;       const int jt = wave;
;       bf16x8 pp[4], vb[4], qa[4], sb[4];
; #pragma unroll
;       for (int ks = 0; ks < 4; ++ks) {
;         pp[ks] = *(const bf16x8*)(Ps + (32 * jt + r) * 144 + ks * 32 + hh * 16);
;         vb[ks] = *(const bf16x8*)(Vts + r * 144 + ks * 32 + hh * 16);
;         qa[ks] = *(const bf16x8*)(Qs + (32 * jt + r) * 272 + ks * 32 + hh * 16);
;         sb[ks] = *(const bf16x8*)(Sts + r * 272 + ks * 32 + hh * 16);
;       }
;       __builtin_amdgcn_sched_barrier(0);
;       f32x16 o, o1;
; #pragma unroll
;       for (int i = 0; i < 16; ++i) { o[i] = 0.f; o1[i] = 0.f; }
; #pragma unroll
;       for (int ks = 0; ks < 4; ++ks) {
;         o = __builtin_amdgcn_mfma_f32_32x32x16_bf16(pp[ks], vb[ks], o, 0, 0, 0);
;         o1 = __builtin_amdgcn_mfma_f32_32x32x16_bf16(qa[ks], sb[ks], o1, 0, 0, 0);
;       }
;       __builtin_amdgcn_sched_barrier(0);
; #pragma unroll
;       for (int ks = 0; ks < 4; ++ks) {
;         qa[ks] = *(const bf16x8*)(Qs + (32 * jt + r) * 272 + (ks + 4) * 32 + hh * 16);
;         sb[ks] = *(const bf16x8*)(Sts + r * 272 + (ks + 4) * 32 + hh * 16);
;       }
;       __builtin_amdgcn_sched_barrier(0);
;       o = __builtin_amdgcn_mfma_f32_32x32x16_bf16(qa[0], sb[0], o, 0, 0, 0);
;       o1 = __builtin_amdgcn_mfma_f32_32x32x16_bf16(qa[1], sb[1], o1, 0, 0, 0);
;       o = __builtin_amdgcn_mfma_f32_32x32x16_bf16(qa[2], sb[2], o, 0, 0, 0);
;       o1 = __builtin_amdgcn_mfma_f32_32x32x16_bf16(qa[3], sb[3], o1, 0, 0, 0);
;       f32x16 o2;
; #pragma unroll
;       for (int i = 0; i < 16; ++i) o2[i] = 0.f;
; #pragma unroll
;       for (int i = 0; i < 8; ++i)
;         opk[i] = pack2(o[2 * i] + o1[2 * i] + o2[2 * i], o[2 * i + 1] + o1[2 * i + 1] + o2[2 * i + 1]);
;       otok = tok0;
.Lsc0_p2efa:
	s_waitcnt lgkmcnt(0)
	s_barrier
	s_cmp_eq_u32 s27, 0
	s_cbranch_scc1 .Lsc0_p3efa
	s_cmp_lt_u32 s9, 2
	s_cbranch_scc0 .Lsc0_p3sfa
	ds_read_b128 v[166:169], v243 offset:53248
	ds_read_b128 v[170:173], v243 offset:53280
	ds_read_b128 v[174:177], v243 offset:53312
	ds_read_b128 v[178:181], v243 offset:53344
	ds_read_b128 v[182:185], v244
	ds_read_b128 v[186:189], v244 offset:32
	ds_read_b128 v[190:193], v244 offset:64
	ds_read_b128 v[194:197], v244 offset:96
	ds_read_b128 v[198:201], v241
	ds_read_b128 v[222:225], v241 offset:32
	ds_read_b128 v[226:229], v241 offset:64
	ds_read_b128 v[230:233], v241 offset:96
	s_waitcnt lgkmcnt(4)
	v_mfma_f32_32x32x16_bf16 v[112:127], v[182:185], v[166:169], 0
	v_mfma_f32_32x32x16_bf16 v[112:127], v[186:189], v[170:173], v[112:127]
	v_mfma_f32_32x32x16_bf16 v[112:127], v[190:193], v[174:177], v[112:127]
	v_mfma_f32_32x32x16_bf16 v[112:127], v[194:197], v[178:181], v[112:127]
	ds_read_b128 v[166:169], v245 offset:4608
	ds_read_b128 v[170:173], v245 offset:4640
	ds_read_b128 v[174:177], v245 offset:4672
	ds_read_b128 v[178:181], v245 offset:4704
	s_waitcnt lgkmcnt(0)
	v_mfma_f32_32x32x16_bf16 v[112:127], v[166:169], v[198:201], v[112:127]
	v_mfma_f32_32x32x16_bf16 v[112:127], v[170:173], v[222:225], v[112:127]
	v_mfma_f32_32x32x16_bf16 v[112:127], v[174:177], v[226:229], v[112:127]
	v_mfma_f32_32x32x16_bf16 v[112:127], v[178:181], v[230:233], v[112:127]
	ds_read_b128 v[198:201], v241 offset:128
	ds_read_b128 v[222:225], v241 offset:160
	ds_read_b128 v[226:229], v241 offset:192
	ds_read_b128 v[230:233], v241 offset:224
	ds_read_b128 v[182:185], v245 offset:4736
	ds_read_b128 v[186:189], v245 offset:4768
	ds_read_b128 v[190:193], v245 offset:4800
	ds_read_b128 v[194:197], v245 offset:4832
	s_waitcnt lgkmcnt(0)
	v_mfma_f32_32x32x16_bf16 v[112:127], v[182:185], v[198:201], v[112:127]
	v_mfma_f32_32x32x16_bf16 v[112:127], v[186:189], v[222:225], v[112:127]
	v_mfma_f32_32x32x16_bf16 v[112:127], v[190:193], v[226:229], v[112:127]
	v_mfma_f32_32x32x16_bf16 v[112:127], v[194:197], v[230:233], v[112:127]
	s_nop 7
	s_nop 7
	v_cvt_pk_bf16_f32 v112, v112, v113
	v_cvt_pk_bf16_f32 v113, v114, v115
	global_store_dwordx2 v217, v[112:113], s[22:23] offset:0
	v_cvt_pk_bf16_f32 v116, v116, v117
	v_cvt_pk_bf16_f32 v117, v118, v119
	global_store_dwordx2 v217, v[116:117], s[22:23] offset:16
	v_cvt_pk_bf16_f32 v120, v120, v121
	v_cvt_pk_bf16_f32 v121, v122, v123
	global_store_dwordx2 v217, v[120:121], s[22:23] offset:32
	v_cvt_pk_bf16_f32 v124, v124, v125
	v_cvt_pk_bf16_f32 v125, v126, v127
	global_store_dwordx2 v217, v[124:125], s[22:23] offset:48
	s_branch .Lsc0_p3efa

; DEV void scan_item_mfma(const Params& p, int g, int item, char* smem) {
;     ...
;     {
;       char* d = Qs + qrow * 272 + qc * 16;
;       *(uint4*)(d) = q0; *(uint4*)(d + 16 * 272) = q1; *(uint4*)(d + 32 * 272) = q2; *(uint4*)(d + 48 * 272) = q3;
;       d = Ks + qrow * 272 + qc * 16;
;       *(uint4*)(d) = k0; *(uint4*)(d + 16 * 272) = k1; *(uint4*)(d + 32 * 272) = k2; *(uint4*)(d + 48 * 272) = k3;
;       d = KTs + trow * 144 + tc * 16;
;       *(uint4*)(d) = t0; *(uint4*)(d + 32 * 144) = t1; *(uint4*)(d + 64 * 144) = t2; *(uint4*)(d + 96 * 144) = t3;
;       st8t(Vts + (vc * 8) * 144 + vrow * 2, vv);
;       if (tid < 128) decs[tid] = dd;
;       if (wave < 2 && ci > 0) {
;         u16* og = PHG + (otok + 32 * wave + 4 * hh) * 2560 + ocol + r;
; #pragma unroll
;         for (int i = 0; i < 8; ++i) {
;           og[(size_t)(((2 * i) & 3) + 8 * ((2 * i) >> 2)) * 2560] = (u16)(opk[i] & 0xffffu);
;           og[(size_t)(((2 * i + 1) & 3) + 8 * ((2 * i + 1) >> 2)) * 2560] = (u16)(opk[i] >> 16);
;         }
;       }
;       if (wave >= 2 && ci > 0) {
; #pragma unroll
;         for (int t = 0; t < 2; ++t) {
;           const int kt = 2 * (wave - 2) + t;
; #pragma unroll
;           for (int rg = 0; rg < 4; ++rg) {
;             const int kk0 = 32 * kt + 8 * rg + 4 * hh;
;             *(uint2*)(Sts + r * 272 + kk0 * 2) = make_uint2(pack2(accS[t][4 * rg + 0], accS[t][4 * rg + 1]),
;                                                             pack2(accS[t][4 * rg + 2], accS[t][4 * rg + 3]));
;           }
;         }
;       }
.Lsc0_w1efb:
	ds_write_b128 v234, v[32:35] offset:0
	ds_write_b128 v234, v[36:39] offset:8704
	ds_write_b128 v234, v[40:43] offset:17408
	ds_write_b128 v234, v[44:47] offset:26112
	ds_write_b128 v235, v[48:51] offset:34816
	ds_write_b128 v235, v[52:55] offset:44032
	s_cmp_eq_u32 s27, 0
	s_cbranch_scc1 .Lsc0_p1ofb
	ds_write_b16 v236, v56 offset:0
	ds_write_b16_d16_hi v236, v56 offset:144
	ds_write_b16 v236, v57 offset:288
	ds_write_b16_d16_hi v236, v57 offset:432
	ds_write_b16 v236, v58 offset:576
	ds_write_b16_d16_hi v236, v58 offset:720
	ds_write_b16 v236, v59 offset:864
	ds_write_b16_d16_hi v236, v59 offset:1008
	ds_write_b32 v237, v60 offset:13312
	s_cmp_lt_u32 s9, 2
	s_cbranch_scc1 .Lsc0_p1ofb
	v_cvt_pk_bf16_f32 v166, v112, v113
	v_cvt_pk_bf16_f32 v167, v114, v115
	ds_write_b64 v238, v[166:167] offset:4608
	v_cvt_pk_bf16_f32 v168, v116, v117
	v_cvt_pk_bf16_f32 v169, v118, v119
	ds_write_b64 v238, v[168:169] offset:4624
	v_cvt_pk_bf16_f32 v170, v120, v121
	v_cvt_pk_bf16_f32 v171, v122, v123
	ds_write_b64 v238, v[170:171] offset:4640
	v_cvt_pk_bf16_f32 v172, v124, v125
	v_cvt_pk_bf16_f32 v173, v126, v127
	ds_write_b64 v238, v[172:173] offset:4656
	v_cvt_pk_bf16_f32 v174, v128, v129
	v_cvt_pk_bf16_f32 v175, v130, v131
	ds_write_b64 v238, v[174:175] offset:4672
	v_cvt_pk_bf16_f32 v176, v132, v133
	v_cvt_pk_bf16_f32 v177, v134, v135
	ds_write_b64 v238, v[176:177] offset:4688
	v_cvt_pk_bf16_f32 v178, v136, v137
	v_cvt_pk_bf16_f32 v179, v138, v139
	ds_write_b64 v238, v[178:179] offset:4704
	v_cvt_pk_bf16_f32 v180, v140, v141
	v_cvt_pk_bf16_f32 v181, v142, v143
	ds_write_b64 v238, v[180:181] offset:4720

; DEV void scan_item_mfma(const Params& p, int g, int item, char* smem) {
;     ...
;   unsigned opk[8] = {0u, 0u, 0u, 0u, 0u, 0u, 0u, 0u};
;   size_t otok = 0;
;   SCAN_ISSUE(dir ? NC - 1 : 0);
.Lsc1_nz:
	s_mov_b32 s25, s9
	s_cmp_eq_u32 s9, 2
	s_cselect_b32 s25, 4, s25
	s_cmp_eq_u32 s26, 0
	s_cselect_b32 s25, s25, 4
	s_cmp_eq_u32 s27, 0
	s_cselect_b32 s0, 2, 0
	s_or_b32 s9, s9, s0
	global_load_dwordx4 v[0:3], v209, s[12:13]
	global_load_dwordx4 v[4:7], v210, s[12:13]
	global_load_dwordx4 v[8:11], v209, s[14:15]
	global_load_dwordx4 v[12:15], v210, s[14:15]
	global_load_dwordx4 v[16:19], v213, s[16:17]
	global_load_dwordx4 v[20:23], v214, s[16:17]
	global_load_dwordx4 v[24:27], v215, s[18:19]
	global_load_dword v28, v216, s[20:21]
	s_sub_i32 s10, s7, 1
	s_cmp_gt_i32 s10, 0
	s_cselect_b32 s1, 1, 0
	s_sub_i32 s10, s10, s1
	s_mul_i32 s0, s1, 0x10000
	s_sub_u32 s12, s12, s0
	s_subb_u32 s13, s13, 0
	s_mul_i32 s0, s1, 0x10000
	s_sub_u32 s14, s14, s0
	s_subb_u32 s15, s15, 0
	s_mul_i32 s0, s1, 0x20000
	s_sub_u32 s16, s16, s0
	s_subb_u32 s17, s17, 0
	s_mul_i32 s0, s1, 0x50000
	s_sub_u32 s18, s18, s0
	s_subb_u32 s19, s19, 0
	s_mul_i32 s0, s1, 0x800
	s_sub_u32 s20, s20, s0
	s_subb_u32 s21, s21, 0
	global_load_dwordx4 v[32:35], v209, s[12:13]
	global_load_dwordx4 v[36:39], v210, s[12:13]
	global_load_dwordx4 v[40:43], v209, s[14:15]
	global_load_dwordx4 v[44:47], v210, s[14:15]
	global_load_dwordx4 v[48:51], v213, s[16:17]
	global_load_dwordx4 v[52:55], v214, s[16:17]
	global_load_dwordx4 v[56:59], v215, s[18:19]
	global_load_dword v60, v216, s[20:21]
	s_cmp_lt_u32 s9, 2
	s_cbranch_scc0 .Lsc1_w1sfa
	s_waitcnt vmcnt(8)
	s_branch .Lsc1_w1efa
